# P9 epilogue: sumsq loads hoisted/prefetched, no vmcnt(0) between row groups
# speedup vs baseline: 1.0021x; 1.0021x over previous
;     __host__ __device__ bool next(int i, Unit& u) const {
;         const long L = (long)i * G + c; if (L >= nwg) return false;
;         int wgid = (int)L; { const int q = nwg / NXCD, r = nwg % NXCD, xcd = wgid % NXCD, off = wgid / NXCD; wgid = (xcd < r ? xcd * (q + 1) : r * (q + 1) + (xcd - r) * q) + off; }
;         const int nig = WGM * nN, gid = wgid / nig, fm = gid * WGM, gsz = (nM - fm) < WGM ? (nM - fm) : WGM;
;         u.pm = fm + ((wgid % nig) % gsz); u.pn = (wgid % nig) / gsz; return true;
;     DI void operator()(Acc& acc, const Unit& u, int wr, int wc, int fr, int fq, LAS unsigned char*) const {
;     ...
;             for (int m = 0; m < 4; ++m) { const int row = u.pm * BM + ai * HALF + wr * 64 + m * 16 + fr; bf16_t* rowp = O + (size_t)row * ldc + col0;
;                 float rs = 1.0f; if (HAS_RS) { const f32x4 q4 = *(const f32x4*)(sumsq + (size_t)row * 4); rs = rsqrtf(((q4.x + q4.y) + (q4.z + q4.w)) * (1.0f / DM) + EPS); }
.LBB0_1068:
	v_lshl_add_u32 v250, s20, 8, v148
	v_mov_b32_e32 v251, 0
	v_lshl_add_u64 v[250:251], v[250:251], 4, s[8:9]
	global_load_dwordx4 v[232:235], v[250:251], off
	global_load_dwordx4 v[236:239], v[250:251], off offset:256
	global_load_dwordx4 v[240:243], v[250:251], off offset:512
	global_load_dwordx4 v[244:247], v[250:251], off offset:768
	s_add_i32 s33, s33, 1
	s_mul_i32 s14, s33, s11
	s_mul_hi_u32 s21, s33, s10
	s_add_i32 s21, s21, s14
	s_mul_i32 s14, s33, s10
	s_add_u32 s34, s14, s2
	s_addc_u32 s35, s21, s3
	v_cmp_gt_i64_e32 vcc, s[34:35], v[142:143]
	v_cmp_lt_i64_e64 s[40:41], s[34:35], v[140:141]
	s_cbranch_vccnz .LBB0_1074
	s_ashr_i32 s14, s34, 31
	s_lshr_b32 s14, s14, 29
	s_add_i32 s14, s34, s14
	s_and_b32 s21, s14, -8
	s_sub_i32 s21, s34, s21
	s_cmp_gt_i32 s21, -1
	s_mov_b64 s[30:31], -1
	s_cbranch_scc0 .LBB0_1071
	s_lshl_b32 s34, s21, 8
	s_mov_b64 s[30:31], 0

; #define PG8_STAGE(bufoff, gbase, voff) do { _Pragma("unroll") for (int _i = 0; _i < 2; ++_i) \
;         __builtin_amdgcn_global_load_lds((const unsigned*)((const char*)(gbase) + (voff)[_i]), (LAS unsigned*)(lds + (bufoff) + ldsw + _i * 8192), 16, 0, 0); } while (0)
; #define PG8_LDA(dst, b, h) do { _Pragma("unroll") for (int m = 0; m < 4; ++m) _Pragma("unroll") for (int k = 0; k < 2; ++k) dst[m][k] = *(const LAS bf16x8*)(lds + PG8_SA(b, h) + aoff + m * 2048 + k * 1024); } while (0)
; #define PG8_LDB(dst, b, h) do { _Pragma("unroll") for (int n = 0; n < 2; ++n) _Pragma("unroll") for (int k = 0; k < 2; ++k) dst[n][k] = *(const LAS bf16x8*)(lds + PG8_SB(b, h) + boff + n * 2048 + k * 1024); } while (0)
; #define PG8_MMA(ai, bj, At, Bt) do { __builtin_amdgcn_s_setprio(1); _Pragma("unroll") for (int m = 0; m < 4; ++m) _Pragma("unroll") for (int n = 0; n < 2; ++n) _Pragma("unroll") for (int k = 0; k < 2; ++k) \
;         acc[ai][bj][m][n] = __builtin_amdgcn_mfma_f32_16x16x32_bf16(Bt[n][k], At[m][k], acc[ai][bj][m][n], 0, 0, 0); __builtin_amdgcn_s_setprio(0); } while (0)
; #define PG8_WAIT_V(n) asm volatile("s_waitcnt vmcnt(" #n ")" ::: "memory")
; #define PG8_WAIT_L(n) asm volatile("s_waitcnt lgkmcnt(" #n ")" ::: "memory")
; #define PG8_BAR __builtin_amdgcn_s_barrier()
; #define PG8_SCHED __builtin_amdgcn_sched_barrier(0)
; template <class GEO, class Epi>
; __device__ __forceinline__ void gemm_phase(LAS unsigned char* lds, const Gemm g, const StaticOrder& S, const Epi& E) {
;     ...
;             PG8_LDB(B0, 0, 0); PG8_LDB(B1, 0, 1); PG8_SCHED; PG8_LDA(At, 0, 0); PG8_STAGE(PG8_SA(1, 1), a1 + hstepA, voffA);
;             PG8_WAIT_V(8); PG8_WAIT_L(0); PG8_BAR; PG8_MMA(0, 0, At, B0); PG8_MMA(0, 1, At, B1); PG8_BAR; PG8_SCHED;
;             PG8_LDA(At, 0, 1); PG8_STAGE(PG8_SB(0, 0), b2, voffB); PG8_STAGE(PG8_SB(0, 1), b2 + hstepB, voffB); PG8_STAGE(PG8_SA(0, 0), a2, voffA);
.LBB0_1075:
	ds_read_b128 v[144:147], v151
	ds_read_b128 v[156:159], v151 offset:1024
	ds_read_b128 v[166:169], v151 offset:2048
	ds_read_b128 v[170:173], v151 offset:3072
	ds_read_b128 v[174:177], v152
	ds_read_b128 v[178:181], v152 offset:1024
	ds_read_b128 v[182:185], v152 offset:2048
	ds_read_b128 v[186:189], v152 offset:3072
	s_add_u32 s38, s22, 0xfffc0080
	s_addc_u32 s39, s23, -1
	s_cmp_eq_u32 s51, 12
	s_cselect_b32 s47, s21, s39
	s_cselect_b32 s46, s31, s38
	s_cselect_b32 s45, s14, s50
	s_cselect_b32 s44, s48, s49
	v_lshl_add_u64 v[160:161], s[22:23], 0, v[136:137]
	s_add_i32 m0, s1, 0xc000
	ds_read_b128 v[190:193], v153
	ds_read_b128 v[194:197], v153 offset:1024
	ds_read_b128 v[198:201], v153 offset:2048
	ds_read_b128 v[202:205], v153 offset:3072
	ds_read_b128 v[210:213], v153 offset:4096
	ds_read_b128 v[214:217], v153 offset:5120
	ds_read_b128 v[218:221], v153 offset:6144
	ds_read_b128 v[222:225], v153 offset:7168
	global_load_lds_dwordx4 v[160:161], off
	v_lshl_add_u64 v[160:161], s[22:23], 0, v[138:139]
	s_add_i32 m0, s1, 0xe000
	s_nop 0
	global_load_lds_dwordx4 v[160:161], off
	s_waitcnt vmcnt(8)
	s_waitcnt lgkmcnt(0)
	s_barrier
	s_setprio 1
	s_waitcnt lgkmcnt(0)
	v_mfma_f32_16x16x32_bf16 v[124:127], v[144:147], v[190:193], v[124:127]
	v_mfma_f32_16x16x32_bf16 v[120:123], v[166:169], v[190:193], v[120:123]
	v_mfma_f32_16x16x32_bf16 v[108:111], v[144:147], v[198:201], v[108:111]
	v_mfma_f32_16x16x32_bf16 v[104:107], v[166:169], v[198:201], v[104:107]
	v_mfma_f32_16x16x32_bf16 v[92:95], v[144:147], v[210:213], v[92:95]
	v_mfma_f32_16x16x32_bf16 v[88:91], v[166:169], v[210:213], v[88:91]
	v_mfma_f32_16x16x32_bf16 v[76:79], v[144:147], v[218:221], v[76:79]
	v_mfma_f32_16x16x32_bf16 v[72:75], v[166:169], v[218:221], v[72:75]
	v_mfma_f32_16x16x32_bf16 v[124:127], v[156:159], v[194:197], v[124:127]
	v_mfma_f32_16x16x32_bf16 v[120:123], v[170:173], v[194:197], v[120:123]
	v_mfma_f32_16x16x32_bf16 v[108:111], v[156:159], v[202:205], v[108:111]
	v_mfma_f32_16x16x32_bf16 v[104:107], v[170:173], v[202:205], v[104:107]
	v_mfma_f32_16x16x32_bf16 v[92:95], v[156:159], v[214:217], v[92:95]
	v_mfma_f32_16x16x32_bf16 v[88:91], v[170:173], v[214:217], v[88:91]
	v_mfma_f32_16x16x32_bf16 v[76:79], v[156:159], v[222:225], v[76:79]
	v_mfma_f32_16x16x32_bf16 v[72:75], v[170:173], v[222:225], v[72:75]
	s_setprio 0
	s_setprio 1
	v_mfma_f32_16x16x32_bf16 v[116:119], v[174:177], v[190:193], v[116:119]
	v_mfma_f32_16x16x32_bf16 v[112:115], v[182:185], v[190:193], v[112:115]
	v_mfma_f32_16x16x32_bf16 v[100:103], v[174:177], v[198:201], v[100:103]
	v_mfma_f32_16x16x32_bf16 v[96:99], v[182:185], v[198:201], v[96:99]
	v_mfma_f32_16x16x32_bf16 v[84:87], v[174:177], v[210:213], v[84:87]
	v_mfma_f32_16x16x32_bf16 v[80:83], v[182:185], v[210:213], v[80:83]
	v_mfma_f32_16x16x32_bf16 v[68:71], v[174:177], v[218:221], v[68:71]
	v_mfma_f32_16x16x32_bf16 v[64:67], v[182:185], v[218:221], v[64:67]
	v_mfma_f32_16x16x32_bf16 v[116:119], v[178:181], v[194:197], v[116:119]
	v_mfma_f32_16x16x32_bf16 v[112:115], v[186:189], v[194:197], v[112:115]
	v_mfma_f32_16x16x32_bf16 v[100:103], v[178:181], v[202:205], v[100:103]
	v_mfma_f32_16x16x32_bf16 v[96:99], v[186:189], v[202:205], v[96:99]
	v_mfma_f32_16x16x32_bf16 v[84:87], v[178:181], v[214:217], v[84:87]
	v_mfma_f32_16x16x32_bf16 v[80:83], v[186:189], v[214:217], v[80:83]
	v_mfma_f32_16x16x32_bf16 v[68:71], v[178:181], v[222:225], v[68:71]
	v_mfma_f32_16x16x32_bf16 v[64:67], v[186:189], v[222:225], v[64:67]
	s_setprio 0
	s_barrier
	s_add_i32 s38, s13, s0
	v_lshl_add_u64 v[160:161], s[44:45], 0, v[132:133]
	s_mov_b32 m0, s38
	ds_read_b128 v[190:193], v153 offset:16384
	ds_read_b128 v[194:197], v153 offset:17408
	ds_read_b128 v[198:201], v153 offset:18432
	ds_read_b128 v[202:205], v153 offset:19456
	ds_read_b128 v[210:213], v153 offset:20480
	ds_read_b128 v[214:217], v153 offset:21504
	ds_read_b128 v[218:221], v153 offset:22528
	ds_read_b128 v[222:225], v153 offset:23552
	global_load_lds_dwordx4 v[160:161], off
	s_add_i32 m0, s38, 0x2000
	s_add_u32 s38, s44, 0x40000
	v_lshl_add_u64 v[206:207], s[44:45], 0, v[128:129]
	s_addc_u32 s39, s45, 0
	s_add_i32 s52, s18, s0
	global_load_lds_dwordx4 v[206:207], off
	v_lshl_add_u64 v[226:227], s[38:39], 0, v[132:133]
	s_mov_b32 m0, s52
	v_lshl_add_u64 v[228:229], s[46:47], 0, v[130:131]
	global_load_lds_dwordx4 v[226:227], off
	v_lshl_add_u64 v[226:227], s[38:39], 0, v[128:129]
	s_add_i32 m0, s52, 0x2000
	s_nop 0
	global_load_lds_dwordx4 v[226:227], off
	v_lshl_add_u64 v[226:227], s[46:47], 0, v[134:135]
	s_mov_b32 m0, s1
	s_nop 0
	global_load_lds_dwordx4 v[226:227], off
	s_mov_b32 m0, s4
	s_nop 0
	global_load_lds_dwordx4 v[228:229], off
	s_waitcnt vmcnt(8)
	s_waitcnt lgkmcnt(0)
	s_barrier
; #define PG8_STAGE(bufoff, gbase, voff) do { _Pragma("unroll") for (int _i = 0; _i < 2; ++_i) \
;         __builtin_amdgcn_global_load_lds((const unsigned*)((const char*)(gbase) + (voff)[_i]), (LAS unsigned*)(lds + (bufoff) + ldsw + _i * 8192), 16, 0, 0); } while (0)
; #define PG8_LDA(dst, b, h) do { _Pragma("unroll") for (int m = 0; m < 4; ++m) _Pragma("unroll") for (int k = 0; k < 2; ++k) dst[m][k] = *(const LAS bf16x8*)(lds + PG8_SA(b, h) + aoff + m * 2048 + k * 1024); } while (0)
; #define PG8_LDB(dst, b, h) do { _Pragma("unroll") for (int n = 0; n < 2; ++n) _Pragma("unroll") for (int k = 0; k < 2; ++k) dst[n][k] = *(const LAS bf16x8*)(lds + PG8_SB(b, h) + boff + n * 2048 + k * 1024); } while (0)
; #define PG8_MMA(ai, bj, At, Bt) do { __builtin_amdgcn_s_setprio(1); _Pragma("unroll") for (int m = 0; m < 4; ++m) _Pragma("unroll") for (int n = 0; n < 2; ++n) _Pragma("unroll") for (int k = 0; k < 2; ++k) \
;         acc[ai][bj][m][n] = __builtin_amdgcn_mfma_f32_16x16x32_bf16(Bt[n][k], At[m][k], acc[ai][bj][m][n], 0, 0, 0); __builtin_amdgcn_s_setprio(0); } while (0)
; #define PG8_WAIT_V(n) asm volatile("s_waitcnt vmcnt(" #n ")" ::: "memory")
; #define PG8_WAIT_L(n) asm volatile("s_waitcnt lgkmcnt(" #n ")" ::: "memory")
; #define PG8_BAR __builtin_amdgcn_s_barrier()
; #define PG8_SCHED __builtin_amdgcn_sched_barrier(0)
; template <class GEO, class Epi>
; __device__ __forceinline__ void gemm_phase(LAS unsigned char* lds, const Gemm g, const StaticOrder& S, const Epi& E) {
;     ...
;             PG8_WAIT_V(8); PG8_WAIT_L(0); PG8_BAR; PG8_MMA(1, 0, At, B0); PG8_MMA(1, 1, At, B1); PG8_BAR; PG8_SCHED;
;             PG8_LDB(B0, 1, 0); PG8_LDB(B1, 1, 1); PG8_SCHED; PG8_LDA(At, 1, 0); PG8_STAGE(PG8_SA(0, 1), a2 + hstepA, voffA);
;             PG8_WAIT_V(8); PG8_WAIT_L(0); PG8_BAR; PG8_MMA(0, 0, At, B0); PG8_MMA(0, 1, At, B1); PG8_BAR; PG8_SCHED;
	s_setprio 1
	s_waitcnt lgkmcnt(0)
	v_mfma_f32_16x16x32_bf16 v[60:63], v[144:147], v[190:193], v[60:63]
	v_mfma_f32_16x16x32_bf16 v[56:59], v[166:169], v[190:193], v[56:59]
	v_mfma_f32_16x16x32_bf16 v[44:47], v[144:147], v[198:201], v[44:47]
	v_mfma_f32_16x16x32_bf16 v[40:43], v[166:169], v[198:201], v[40:43]
	v_mfma_f32_16x16x32_bf16 v[28:31], v[144:147], v[210:213], v[28:31]
	v_mfma_f32_16x16x32_bf16 v[24:27], v[166:169], v[210:213], v[24:27]
	v_mfma_f32_16x16x32_bf16 v[12:15], v[144:147], v[218:221], v[12:15]
	v_mfma_f32_16x16x32_bf16 v[8:11], v[166:169], v[218:221], v[8:11]
	v_mfma_f32_16x16x32_bf16 v[60:63], v[156:159], v[194:197], v[60:63]
	v_mfma_f32_16x16x32_bf16 v[56:59], v[170:173], v[194:197], v[56:59]
	v_mfma_f32_16x16x32_bf16 v[44:47], v[156:159], v[202:205], v[44:47]
	v_mfma_f32_16x16x32_bf16 v[40:43], v[170:173], v[202:205], v[40:43]
	v_mfma_f32_16x16x32_bf16 v[28:31], v[156:159], v[214:217], v[28:31]
	v_mfma_f32_16x16x32_bf16 v[24:27], v[170:173], v[214:217], v[24:27]
	v_mfma_f32_16x16x32_bf16 v[12:15], v[156:159], v[222:225], v[12:15]
	v_mfma_f32_16x16x32_bf16 v[8:11], v[170:173], v[222:225], v[8:11]
	s_setprio 0
	s_setprio 1
	v_mfma_f32_16x16x32_bf16 v[52:55], v[174:177], v[190:193], v[52:55]
	v_mfma_f32_16x16x32_bf16 v[48:51], v[182:185], v[190:193], v[48:51]
	v_mfma_f32_16x16x32_bf16 v[36:39], v[174:177], v[198:201], v[36:39]
	v_mfma_f32_16x16x32_bf16 v[32:35], v[182:185], v[198:201], v[32:35]
	v_mfma_f32_16x16x32_bf16 v[20:23], v[174:177], v[210:213], v[20:23]
	v_mfma_f32_16x16x32_bf16 v[16:19], v[182:185], v[210:213], v[16:19]
	v_mfma_f32_16x16x32_bf16 v[4:7], v[174:177], v[218:221], v[4:7]
	v_mfma_f32_16x16x32_bf16 v[0:3], v[182:185], v[218:221], v[0:3]
	v_mfma_f32_16x16x32_bf16 v[52:55], v[178:181], v[194:197], v[52:55]
	v_mfma_f32_16x16x32_bf16 v[48:51], v[186:189], v[194:197], v[48:51]
	v_mfma_f32_16x16x32_bf16 v[36:39], v[178:181], v[202:205], v[36:39]
	v_mfma_f32_16x16x32_bf16 v[32:35], v[186:189], v[202:205], v[32:35]
	v_mfma_f32_16x16x32_bf16 v[20:23], v[178:181], v[214:217], v[20:23]
	v_mfma_f32_16x16x32_bf16 v[16:19], v[186:189], v[214:217], v[16:19]
	v_mfma_f32_16x16x32_bf16 v[4:7], v[178:181], v[222:225], v[4:7]
	v_mfma_f32_16x16x32_bf16 v[0:3], v[186:189], v[222:225], v[0:3]
	s_setprio 0
	s_barrier
	s_add_i32 s52, 0, 0x18000
	v_add_u32_e32 v155, s52, v149
	s_add_i32 s53, 0, 0x1c000
	ds_read_b128 v[144:147], v155
	ds_read_b128 v[156:159], v155 offset:1024
	ds_read_b128 v[166:169], v155 offset:2048
	ds_read_b128 v[170:173], v155 offset:3072
	v_add_u32_e32 v155, s53, v149
	ds_read_b128 v[174:177], v155
	ds_read_b128 v[178:181], v155 offset:1024
	ds_read_b128 v[182:185], v155 offset:2048
	ds_read_b128 v[186:189], v155 offset:3072
	s_add_u32 s38, s46, 0x40000
	s_addc_u32 s39, s47, 0
	s_mov_b32 m0, s5
	v_lshl_add_u64 v[230:231], s[38:39], 0, v[134:135]
	ds_read_b128 v[190:193], v153 offset:32768
	ds_read_b128 v[194:197], v153 offset:33792
	ds_read_b128 v[198:201], v153 offset:34816
	ds_read_b128 v[202:205], v153 offset:35840
	ds_read_b128 v[210:213], v153 offset:36864
	ds_read_b128 v[214:217], v153 offset:37888
	ds_read_b128 v[218:221], v153 offset:38912
	ds_read_b128 v[222:225], v153 offset:39936
	global_load_lds_dwordx4 v[230:231], off
	v_lshl_add_u64 v[230:231], s[38:39], 0, v[130:131]
	s_mov_b32 m0, s6
	s_nop 0
	global_load_lds_dwordx4 v[230:231], off
	s_waitcnt vmcnt(8)
	s_waitcnt lgkmcnt(0)
	s_barrier
	s_setprio 1
	s_waitcnt lgkmcnt(0)
	v_mfma_f32_16x16x32_bf16 v[124:127], v[144:147], v[190:193], v[124:127]
	v_mfma_f32_16x16x32_bf16 v[120:123], v[166:169], v[190:193], v[120:123]
	v_mfma_f32_16x16x32_bf16 v[108:111], v[144:147], v[198:201], v[108:111]
	v_mfma_f32_16x16x32_bf16 v[104:107], v[166:169], v[198:201], v[104:107]
	v_mfma_f32_16x16x32_bf16 v[92:95], v[144:147], v[210:213], v[92:95]
	v_mfma_f32_16x16x32_bf16 v[88:91], v[166:169], v[210:213], v[88:91]
	v_mfma_f32_16x16x32_bf16 v[76:79], v[144:147], v[218:221], v[76:79]
	v_mfma_f32_16x16x32_bf16 v[72:75], v[166:169], v[218:221], v[72:75]
	v_mfma_f32_16x16x32_bf16 v[124:127], v[156:159], v[194:197], v[124:127]
	v_mfma_f32_16x16x32_bf16 v[120:123], v[170:173], v[194:197], v[120:123]
	v_mfma_f32_16x16x32_bf16 v[108:111], v[156:159], v[202:205], v[108:111]
	v_mfma_f32_16x16x32_bf16 v[104:107], v[170:173], v[202:205], v[104:107]
	v_mfma_f32_16x16x32_bf16 v[92:95], v[156:159], v[214:217], v[92:95]
	v_mfma_f32_16x16x32_bf16 v[88:91], v[170:173], v[214:217], v[88:91]
	v_mfma_f32_16x16x32_bf16 v[76:79], v[156:159], v[222:225], v[76:79]
	v_mfma_f32_16x16x32_bf16 v[72:75], v[170:173], v[222:225], v[72:75]
	s_setprio 0
	s_setprio 1
	v_mfma_f32_16x16x32_bf16 v[116:119], v[174:177], v[190:193], v[116:119]
	v_mfma_f32_16x16x32_bf16 v[112:115], v[182:185], v[190:193], v[112:115]
	v_mfma_f32_16x16x32_bf16 v[100:103], v[174:177], v[198:201], v[100:103]
	v_mfma_f32_16x16x32_bf16 v[96:99], v[182:185], v[198:201], v[96:99]
	v_mfma_f32_16x16x32_bf16 v[84:87], v[174:177], v[210:213], v[84:87]
	v_mfma_f32_16x16x32_bf16 v[80:83], v[182:185], v[210:213], v[80:83]
	v_mfma_f32_16x16x32_bf16 v[68:71], v[174:177], v[218:221], v[68:71]
	v_mfma_f32_16x16x32_bf16 v[64:67], v[182:185], v[218:221], v[64:67]
	v_mfma_f32_16x16x32_bf16 v[116:119], v[178:181], v[194:197], v[116:119]
	v_mfma_f32_16x16x32_bf16 v[112:115], v[186:189], v[194:197], v[112:115]
	v_mfma_f32_16x16x32_bf16 v[100:103], v[178:181], v[202:205], v[100:103]
	v_mfma_f32_16x16x32_bf16 v[96:99], v[186:189], v[202:205], v[96:99]
	v_mfma_f32_16x16x32_bf16 v[84:87], v[178:181], v[214:217], v[84:87]
	v_mfma_f32_16x16x32_bf16 v[80:83], v[186:189], v[214:217], v[80:83]
	v_mfma_f32_16x16x32_bf16 v[68:71], v[178:181], v[222:225], v[68:71]
	v_mfma_f32_16x16x32_bf16 v[64:67], v[186:189], v[222:225], v[64:67]
	s_setprio 0
	s_barrier
; #define PG8_STAGE(bufoff, gbase, voff) do { _Pragma("unroll") for (int _i = 0; _i < 2; ++_i) \
;         __builtin_amdgcn_global_load_lds((const unsigned*)((const char*)(gbase) + (voff)[_i]), (LAS unsigned*)(lds + (bufoff) + ldsw + _i * 8192), 16, 0, 0); } while (0)
; #define PG8_LDA(dst, b, h) do { _Pragma("unroll") for (int m = 0; m < 4; ++m) _Pragma("unroll") for (int k = 0; k < 2; ++k) dst[m][k] = *(const LAS bf16x8*)(lds + PG8_SA(b, h) + aoff + m * 2048 + k * 1024); } while (0)
; #define PG8_MMA(ai, bj, At, Bt) do { __builtin_amdgcn_s_setprio(1); _Pragma("unroll") for (int m = 0; m < 4; ++m) _Pragma("unroll") for (int n = 0; n < 2; ++n) _Pragma("unroll") for (int k = 0; k < 2; ++k) \
;         acc[ai][bj][m][n] = __builtin_amdgcn_mfma_f32_16x16x32_bf16(Bt[n][k], At[m][k], acc[ai][bj][m][n], 0, 0, 0); __builtin_amdgcn_s_setprio(0); } while (0)
; #define PG8_WAIT_V(n) asm volatile("s_waitcnt vmcnt(" #n ")" ::: "memory")
; #define PG8_WAIT_L(n) asm volatile("s_waitcnt lgkmcnt(" #n ")" ::: "memory")
; #define PG8_BAR __builtin_amdgcn_s_barrier()
; #define PG8_SCHED __builtin_amdgcn_sched_barrier(0)
;     DI void operator()(Acc& acc, const Unit& u, int wr, int wc, int fr, int fq, LAS unsigned char*) const {
;     ...
;             for (int m = 0; m < 4; ++m) { const int row = u.pm * BM + ai * HALF + wr * 64 + m * 16 + fr; bf16_t* rowp = O + (size_t)row * ldc + col0;
;                 float rs = 1.0f; if (HAS_RS) { const f32x4 q4 = *(const f32x4*)(sumsq + (size_t)row * 4); rs = rsqrtf(((q4.x + q4.y) + (q4.z + q4.w)) * (1.0f / DM) + EPS); }
; #pragma unroll
;                 for (int bj = 0; bj < 2; ++bj) { f32x4 v0 = acc[ai][bj][m][0] * rs, v1 = acc[ai][bj][m][1] * rs;
;                     if (act) { v0 = __builtin_elementwise_max(v0, (f32x4){0.f, 0.f, 0.f, 0.f}); v1 = __builtin_elementwise_max(v1, (f32x4){0.f, 0.f, 0.f, 0.f}); v0 = v0 * v0; v1 = v1 * v1; }
; template <class GEO, class Epi>
; __device__ __forceinline__ void gemm_phase(LAS unsigned char* lds, const Gemm g, const StaticOrder& S, const Epi& E) {
;     ...
;             PG8_LDA(At, 1, 1); PG8_STAGE(PG8_SB(1, 0), b3, voffB); PG8_STAGE(PG8_SB(1, 1), b3 + hstepB, voffB); PG8_STAGE(PG8_SA(1, 0), a3, voffA);
;             PG8_WAIT_V(8); PG8_WAIT_L(0); PG8_BAR; PG8_MMA(1, 0, At, B0); PG8_MMA(1, 1, At, B1); PG8_BAR; PG8_SCHED;
;         }
;         if (wr == 0) PG8_BAR;
	s_add_i32 s38, s52, s0
	v_lshl_add_u64 v[160:161], v[160:161], 0, s[24:25]
	s_mov_b32 m0, s38
	ds_read_b128 v[190:193], v153 offset:49152
	ds_read_b128 v[194:197], v153 offset:50176
	ds_read_b128 v[198:201], v153 offset:51200
	ds_read_b128 v[202:205], v153 offset:52224
	ds_read_b128 v[210:213], v153 offset:53248
	ds_read_b128 v[214:217], v153 offset:54272
	ds_read_b128 v[218:221], v153 offset:55296
	ds_read_b128 v[222:225], v153 offset:56320
	global_load_lds_dwordx4 v[160:161], off
	s_add_i32 m0, s38, 0x2000
	s_add_u32 s38, s44, 0x40080
	v_lshl_add_u64 v[160:161], v[206:207], 0, s[24:25]
	s_addc_u32 s39, s45, 0
	s_add_i32 s44, s53, s0
	global_load_lds_dwordx4 v[160:161], off
	v_lshl_add_u64 v[160:161], s[38:39], 0, v[132:133]
	s_mov_b32 m0, s44
	s_nop 0
	global_load_lds_dwordx4 v[160:161], off
	v_lshl_add_u64 v[160:161], s[38:39], 0, v[128:129]
	s_add_i32 m0, s44, 0x2000
	s_nop 0
	global_load_lds_dwordx4 v[160:161], off
	v_lshl_add_u64 v[160:161], v[226:227], 0, s[24:25]
	s_mov_b32 m0, s7
	s_nop 0
	global_load_lds_dwordx4 v[160:161], off
	v_lshl_add_u64 v[160:161], v[228:229], 0, s[24:25]
	s_mov_b32 m0, s12
	s_nop 0
	global_load_lds_dwordx4 v[160:161], off
	s_waitcnt vmcnt(8)
	s_waitcnt lgkmcnt(0)
	s_barrier
	s_setprio 1
	s_waitcnt lgkmcnt(0)
	v_mfma_f32_16x16x32_bf16 v[60:63], v[144:147], v[190:193], v[60:63]
	v_mfma_f32_16x16x32_bf16 v[56:59], v[166:169], v[190:193], v[56:59]
	v_mfma_f32_16x16x32_bf16 v[44:47], v[144:147], v[198:201], v[44:47]
	v_mfma_f32_16x16x32_bf16 v[40:43], v[166:169], v[198:201], v[40:43]
	v_mfma_f32_16x16x32_bf16 v[28:31], v[144:147], v[210:213], v[28:31]
	v_mfma_f32_16x16x32_bf16 v[24:27], v[166:169], v[210:213], v[24:27]
	v_mfma_f32_16x16x32_bf16 v[12:15], v[144:147], v[218:221], v[12:15]
	v_mfma_f32_16x16x32_bf16 v[8:11], v[166:169], v[218:221], v[8:11]
	v_mfma_f32_16x16x32_bf16 v[60:63], v[156:159], v[194:197], v[60:63]
	v_mfma_f32_16x16x32_bf16 v[56:59], v[170:173], v[194:197], v[56:59]
	v_mfma_f32_16x16x32_bf16 v[44:47], v[156:159], v[202:205], v[44:47]
	v_mfma_f32_16x16x32_bf16 v[40:43], v[170:173], v[202:205], v[40:43]
	v_mfma_f32_16x16x32_bf16 v[28:31], v[156:159], v[214:217], v[28:31]
	v_mfma_f32_16x16x32_bf16 v[24:27], v[170:173], v[214:217], v[24:27]
	v_mfma_f32_16x16x32_bf16 v[12:15], v[156:159], v[222:225], v[12:15]
	v_mfma_f32_16x16x32_bf16 v[8:11], v[170:173], v[222:225], v[8:11]
	s_setprio 0
	s_setprio 1
	v_mfma_f32_16x16x32_bf16 v[52:55], v[174:177], v[190:193], v[52:55]
	v_mfma_f32_16x16x32_bf16 v[48:51], v[182:185], v[190:193], v[48:51]
	v_mfma_f32_16x16x32_bf16 v[36:39], v[174:177], v[198:201], v[36:39]
	v_mfma_f32_16x16x32_bf16 v[32:35], v[182:185], v[198:201], v[32:35]
	v_mfma_f32_16x16x32_bf16 v[20:23], v[174:177], v[210:213], v[20:23]
	v_mfma_f32_16x16x32_bf16 v[16:19], v[182:185], v[210:213], v[16:19]
	v_mfma_f32_16x16x32_bf16 v[4:7], v[174:177], v[218:221], v[4:7]
	v_mfma_f32_16x16x32_bf16 v[0:3], v[182:185], v[218:221], v[0:3]
	v_mfma_f32_16x16x32_bf16 v[52:55], v[178:181], v[194:197], v[52:55]
	v_mfma_f32_16x16x32_bf16 v[48:51], v[186:189], v[194:197], v[48:51]
	v_mfma_f32_16x16x32_bf16 v[36:39], v[178:181], v[202:205], v[36:39]
	v_mfma_f32_16x16x32_bf16 v[32:35], v[186:189], v[202:205], v[32:35]
	v_mfma_f32_16x16x32_bf16 v[20:23], v[178:181], v[214:217], v[20:23]
	v_mfma_f32_16x16x32_bf16 v[16:19], v[186:189], v[214:217], v[16:19]
	v_mfma_f32_16x16x32_bf16 v[4:7], v[178:181], v[222:225], v[4:7]
	v_mfma_f32_16x16x32_bf16 v[0:3], v[186:189], v[222:225], v[0:3]
	s_setprio 0
	s_barrier
	s_add_i32 s51, s51, 2
	s_add_u32 s22, s22, 0x100
	s_addc_u32 s23, s23, 0
	s_add_u32 s49, s49, 0x100
	s_addc_u32 s50, s50, 0
	s_cmp_gt_u32 s51, 13
	s_cbranch_scc0 .LBB0_1075
	v_lshl_add_u32 v144, s20, 8, v148
	v_lshl_or_b32 v146, s37, 8, v150
	v_ashrrev_i32_e32 v145, 31, v144
	v_ashrrev_i32_e32 v147, 31, v146
	v_lshl_add_u64 v[156:157], v[144:145], 4, s[8:9]
	global_load_dwordx4 v[166:169], v[156:157], off offset:2048
	global_load_dwordx4 v[170:173], v[156:157], off offset:2304
	global_load_dwordx4 v[174:177], v[156:157], off offset:2560
	global_load_dwordx4 v[178:181], v[156:157], off offset:2816
	s_and_b64 vcc, exec, s[28:29]
	s_cbranch_vccz .LBB0_1078
	s_barrier
.LBB0_1078:
	v_lshlrev_b64 v[158:159], 13, v[144:145]
	v_lshl_add_u64 v[158:159], s[96:97], 0, v[158:159]
	v_lshlrev_b64 v[146:147], 1, v[146:147]
	v_lshl_add_u64 v[160:161], v[158:159], 0, v[146:147]
	s_mov_b64 s[20:21], -1
	s_mov_b32 s44, 0x20000
	s_mov_b32 s45, 0
	s_mov_b32 s46, 0x100000
	s_mov_b32 s47, 0
	v_lshl_add_u64 v[198:199], v[160:161], 0, s[46:47]
	v_add_f32_e32 v182, v232, v233
	v_add_f32_e32 v184, v236, v237
	v_add_f32_e32 v186, v240, v241
	v_add_f32_e32 v188, v244, v245
	v_add_f32_e32 v183, v234, v235
	v_add_f32_e32 v185, v238, v239
	v_add_f32_e32 v187, v242, v243
	v_add_f32_e32 v189, v246, v247
	v_add_f32_e32 v182, v182, v183
	v_add_f32_e32 v184, v184, v185
	v_add_f32_e32 v186, v186, v187
	v_add_f32_e32 v188, v188, v189
	v_fmamk_f32 v182, v182, 0x3a800000, v154
	v_fmamk_f32 v184, v184, 0x3a800000, v154
	v_fmamk_f32 v186, v186, 0x3a800000, v154
	v_fmamk_f32 v188, v188, 0x3a800000, v154
	v_rsq_f32_e32 v182, v182
	v_rsq_f32_e32 v184, v184
	v_rsq_f32_e32 v186, v186
	v_rsq_f32_e32 v188, v188
	v_pk_mul_f32 v[126:127], v[126:127], v[182:183] op_sel_hi:[1,0]
	v_pk_mul_f32 v[124:125], v[124:125], v[182:183] op_sel_hi:[1,0]
	v_pk_mul_f32 v[122:123], v[122:123], v[182:183] op_sel_hi:[1,0]
	v_pk_mul_f32 v[120:121], v[120:121], v[182:183] op_sel_hi:[1,0]
	v_max_f32_e32 v120, 0, v120
	v_max_f32_e32 v121, 0, v121
	v_max_f32_e32 v122, 0, v122
	v_max_f32_e32 v123, 0, v123
	v_max_f32_e32 v124, 0, v124
	v_max_f32_e32 v125, 0, v125
; DI unsigned pk2(float lo, float hi) { f32x2 v = {lo, hi}; bf16x2_t b = __builtin_convertvector(v, bf16x2_t); return __builtin_bit_cast(unsigned, b); }
;     DI void operator()(Acc& acc, const Unit& u, int wr, int wc, int fr, int fq, LAS unsigned char*) const {
;     ...
;             for (int m = 0; m < 4; ++m) { const int row = u.pm * BM + ai * HALF + wr * 64 + m * 16 + fr; bf16_t* rowp = O + (size_t)row * ldc + col0;
;                 float rs = 1.0f; if (HAS_RS) { const f32x4 q4 = *(const f32x4*)(sumsq + (size_t)row * 4); rs = rsqrtf(((q4.x + q4.y) + (q4.z + q4.w)) * (1.0f / DM) + EPS); }
; #pragma unroll
;                 for (int bj = 0; bj < 2; ++bj) { f32x4 v0 = acc[ai][bj][m][0] * rs, v1 = acc[ai][bj][m][1] * rs;
;                     if (act) { v0 = __builtin_elementwise_max(v0, (f32x4){0.f, 0.f, 0.f, 0.f}); v1 = __builtin_elementwise_max(v1, (f32x4){0.f, 0.f, 0.f, 0.f}); v0 = v0 * v0; v1 = v1 * v1; }
;                     u32x4 w; w.x = pk2(v0.x, v0.y); w.y = pk2(v0.z, v0.w); w.z = pk2(v1.x, v1.y); w.w = pk2(v1.z, v1.w);
;                     if (act) __builtin_nontemporal_store(w, (u32x4*)(rowp + bj * HALF)); else *(u32x4*)(rowp + bj * HALF) = w; } }
	v_max_f32_e32 v126, 0, v126
	v_max_f32_e32 v127, 0, v127
	v_pk_mul_f32 v[126:127], v[126:127], v[126:127]
	v_pk_mul_f32 v[124:125], v[124:125], v[124:125]
	v_pk_mul_f32 v[122:123], v[122:123], v[122:123]
	v_pk_mul_f32 v[120:121], v[120:121], v[120:121]
	v_cvt_pk_bf16_f32 v200, v124, v125
	v_cvt_pk_bf16_f32 v201, v126, v127
	v_cvt_pk_bf16_f32 v202, v120, v121
	v_cvt_pk_bf16_f32 v203, v122, v123
	global_store_dwordx4 v[160:161], v[200:203], off nt
	v_pk_mul_f32 v[118:119], v[118:119], v[182:183] op_sel_hi:[1,0]
	v_pk_mul_f32 v[116:117], v[116:117], v[182:183] op_sel_hi:[1,0]
	v_pk_mul_f32 v[114:115], v[114:115], v[182:183] op_sel_hi:[1,0]
	v_pk_mul_f32 v[112:113], v[112:113], v[182:183] op_sel_hi:[1,0]
	v_max_f32_e32 v112, 0, v112
	v_max_f32_e32 v113, 0, v113
	v_max_f32_e32 v114, 0, v114
	v_max_f32_e32 v115, 0, v115
	v_max_f32_e32 v116, 0, v116
	v_max_f32_e32 v117, 0, v117
	v_max_f32_e32 v118, 0, v118
	v_max_f32_e32 v119, 0, v119
	v_pk_mul_f32 v[118:119], v[118:119], v[118:119]
	v_pk_mul_f32 v[116:117], v[116:117], v[116:117]
	v_pk_mul_f32 v[114:115], v[114:115], v[114:115]
	v_pk_mul_f32 v[112:113], v[112:113], v[112:113]
	v_cvt_pk_bf16_f32 v204, v116, v117
	v_cvt_pk_bf16_f32 v205, v118, v119
	v_cvt_pk_bf16_f32 v206, v112, v113
	v_cvt_pk_bf16_f32 v207, v114, v115
	global_store_dwordx4 v[160:161], v[204:207], off offset:256 nt
	v_lshl_add_u64 v[158:159], v[160:161], 0, s[44:45]
	v_pk_mul_f32 v[110:111], v[110:111], v[184:185] op_sel_hi:[1,0]
	v_pk_mul_f32 v[108:109], v[108:109], v[184:185] op_sel_hi:[1,0]
	v_pk_mul_f32 v[106:107], v[106:107], v[184:185] op_sel_hi:[1,0]
	v_pk_mul_f32 v[104:105], v[104:105], v[184:185] op_sel_hi:[1,0]
	v_max_f32_e32 v104, 0, v104
	v_max_f32_e32 v105, 0, v105
	v_max_f32_e32 v106, 0, v106
	v_max_f32_e32 v107, 0, v107
	v_max_f32_e32 v108, 0, v108
	v_max_f32_e32 v109, 0, v109
	v_max_f32_e32 v110, 0, v110
	v_max_f32_e32 v111, 0, v111
	v_pk_mul_f32 v[110:111], v[110:111], v[110:111]
	v_pk_mul_f32 v[108:109], v[108:109], v[108:109]
	v_pk_mul_f32 v[106:107], v[106:107], v[106:107]
	v_pk_mul_f32 v[104:105], v[104:105], v[104:105]
	v_cvt_pk_bf16_f32 v210, v108, v109
	v_cvt_pk_bf16_f32 v211, v110, v111
	v_cvt_pk_bf16_f32 v212, v104, v105
	v_cvt_pk_bf16_f32 v213, v106, v107
	global_store_dwordx4 v[158:159], v[210:213], off nt
	v_pk_mul_f32 v[102:103], v[102:103], v[184:185] op_sel_hi:[1,0]
	v_pk_mul_f32 v[100:101], v[100:101], v[184:185] op_sel_hi:[1,0]
	v_pk_mul_f32 v[98:99], v[98:99], v[184:185] op_sel_hi:[1,0]
	v_pk_mul_f32 v[96:97], v[96:97], v[184:185] op_sel_hi:[1,0]
	v_max_f32_e32 v96, 0, v96
	v_max_f32_e32 v97, 0, v97
	v_max_f32_e32 v98, 0, v98
	v_max_f32_e32 v99, 0, v99
	v_max_f32_e32 v100, 0, v100
	v_max_f32_e32 v101, 0, v101
	v_max_f32_e32 v102, 0, v102
	v_max_f32_e32 v103, 0, v103
	v_pk_mul_f32 v[102:103], v[102:103], v[102:103]
	v_pk_mul_f32 v[100:101], v[100:101], v[100:101]
	v_pk_mul_f32 v[98:99], v[98:99], v[98:99]
	v_pk_mul_f32 v[96:97], v[96:97], v[96:97]
	v_cvt_pk_bf16_f32 v214, v100, v101
	v_cvt_pk_bf16_f32 v215, v102, v103
	v_cvt_pk_bf16_f32 v216, v96, v97
	v_cvt_pk_bf16_f32 v217, v98, v99
	global_store_dwordx4 v[158:159], v[214:217], off offset:256 nt
	v_lshl_add_u64 v[160:161], v[158:159], 0, s[44:45]
	v_pk_mul_f32 v[94:95], v[94:95], v[186:187] op_sel_hi:[1,0]
	v_pk_mul_f32 v[92:93], v[92:93], v[186:187] op_sel_hi:[1,0]
	v_pk_mul_f32 v[90:91], v[90:91], v[186:187] op_sel_hi:[1,0]
	v_pk_mul_f32 v[88:89], v[88:89], v[186:187] op_sel_hi:[1,0]
	v_max_f32_e32 v88, 0, v88
	v_max_f32_e32 v89, 0, v89
	v_max_f32_e32 v90, 0, v90
	v_max_f32_e32 v91, 0, v91
	v_max_f32_e32 v92, 0, v92
	v_max_f32_e32 v93, 0, v93
	v_max_f32_e32 v94, 0, v94
	v_max_f32_e32 v95, 0, v95
	v_pk_mul_f32 v[94:95], v[94:95], v[94:95]
	v_pk_mul_f32 v[92:93], v[92:93], v[92:93]
	v_pk_mul_f32 v[90:91], v[90:91], v[90:91]
	v_pk_mul_f32 v[88:89], v[88:89], v[88:89]
	v_cvt_pk_bf16_f32 v200, v92, v93
	v_cvt_pk_bf16_f32 v201, v94, v95
	v_cvt_pk_bf16_f32 v202, v88, v89
	v_cvt_pk_bf16_f32 v203, v90, v91
	global_store_dwordx4 v[160:161], v[200:203], off nt
	v_pk_mul_f32 v[86:87], v[86:87], v[186:187] op_sel_hi:[1,0]
	v_pk_mul_f32 v[84:85], v[84:85], v[186:187] op_sel_hi:[1,0]
	v_pk_mul_f32 v[82:83], v[82:83], v[186:187] op_sel_hi:[1,0]
	v_pk_mul_f32 v[80:81], v[80:81], v[186:187] op_sel_hi:[1,0]
	v_max_f32_e32 v80, 0, v80
	v_max_f32_e32 v81, 0, v81
	v_max_f32_e32 v82, 0, v82
	v_max_f32_e32 v83, 0, v83
	v_max_f32_e32 v84, 0, v84
	v_max_f32_e32 v85, 0, v85
	v_max_f32_e32 v86, 0, v86
	v_max_f32_e32 v87, 0, v87
	v_pk_mul_f32 v[86:87], v[86:87], v[86:87]
	v_pk_mul_f32 v[84:85], v[84:85], v[84:85]
	v_pk_mul_f32 v[82:83], v[82:83], v[82:83]
	v_pk_mul_f32 v[80:81], v[80:81], v[80:81]
	v_cvt_pk_bf16_f32 v204, v84, v85
	v_cvt_pk_bf16_f32 v205, v86, v87
	v_cvt_pk_bf16_f32 v206, v80, v81
	v_cvt_pk_bf16_f32 v207, v82, v83
	global_store_dwordx4 v[160:161], v[204:207], off offset:256 nt
	v_lshl_add_u64 v[158:159], v[160:161], 0, s[44:45]
	v_pk_mul_f32 v[78:79], v[78:79], v[188:189] op_sel_hi:[1,0]
	v_pk_mul_f32 v[76:77], v[76:77], v[188:189] op_sel_hi:[1,0]
	v_pk_mul_f32 v[74:75], v[74:75], v[188:189] op_sel_hi:[1,0]
	v_pk_mul_f32 v[72:73], v[72:73], v[188:189] op_sel_hi:[1,0]
	v_max_f32_e32 v72, 0, v72
	v_max_f32_e32 v73, 0, v73
	v_max_f32_e32 v74, 0, v74
	v_max_f32_e32 v75, 0, v75
	v_max_f32_e32 v76, 0, v76
	v_max_f32_e32 v77, 0, v77
	v_max_f32_e32 v78, 0, v78
	v_max_f32_e32 v79, 0, v79
	v_pk_mul_f32 v[78:79], v[78:79], v[78:79]
	v_pk_mul_f32 v[76:77], v[76:77], v[76:77]
	v_pk_mul_f32 v[74:75], v[74:75], v[74:75]
	v_pk_mul_f32 v[72:73], v[72:73], v[72:73]
	v_cvt_pk_bf16_f32 v210, v76, v77
	v_cvt_pk_bf16_f32 v211, v78, v79
	v_cvt_pk_bf16_f32 v212, v72, v73
	v_cvt_pk_bf16_f32 v213, v74, v75
	global_store_dwordx4 v[158:159], v[210:213], off nt
	v_pk_mul_f32 v[70:71], v[70:71], v[188:189] op_sel_hi:[1,0]
	v_pk_mul_f32 v[68:69], v[68:69], v[188:189] op_sel_hi:[1,0]
	v_pk_mul_f32 v[66:67], v[66:67], v[188:189] op_sel_hi:[1,0]
	v_pk_mul_f32 v[64:65], v[64:65], v[188:189] op_sel_hi:[1,0]
	v_max_f32_e32 v64, 0, v64
	v_max_f32_e32 v65, 0, v65
	v_max_f32_e32 v66, 0, v66
	v_max_f32_e32 v67, 0, v67
	v_max_f32_e32 v68, 0, v68
	v_max_f32_e32 v69, 0, v69
	v_max_f32_e32 v70, 0, v70
	v_max_f32_e32 v71, 0, v71
	v_pk_mul_f32 v[70:71], v[70:71], v[70:71]
	v_pk_mul_f32 v[68:69], v[68:69], v[68:69]
	v_pk_mul_f32 v[66:67], v[66:67], v[66:67]
	v_pk_mul_f32 v[64:65], v[64:65], v[64:65]
	v_cvt_pk_bf16_f32 v214, v68, v69
	v_cvt_pk_bf16_f32 v215, v70, v71
	v_cvt_pk_bf16_f32 v216, v64, v65
	v_cvt_pk_bf16_f32 v217, v66, v67
	global_store_dwordx4 v[158:159], v[214:217], off offset:256 nt
	s_waitcnt vmcnt(8)
; DI unsigned pk2(float lo, float hi) { f32x2 v = {lo, hi}; bf16x2_t b = __builtin_convertvector(v, bf16x2_t); return __builtin_bit_cast(unsigned, b); }
;     DI void operator()(Acc& acc, const Unit& u, int wr, int wc, int fr, int fq, LAS unsigned char*) const {
;     ...
;             for (int m = 0; m < 4; ++m) { const int row = u.pm * BM + ai * HALF + wr * 64 + m * 16 + fr; bf16_t* rowp = O + (size_t)row * ldc + col0;
;                 float rs = 1.0f; if (HAS_RS) { const f32x4 q4 = *(const f32x4*)(sumsq + (size_t)row * 4); rs = rsqrtf(((q4.x + q4.y) + (q4.z + q4.w)) * (1.0f / DM) + EPS); }
; #pragma unroll
;                 for (int bj = 0; bj < 2; ++bj) { f32x4 v0 = acc[ai][bj][m][0] * rs, v1 = acc[ai][bj][m][1] * rs;
;                     if (act) { v0 = __builtin_elementwise_max(v0, (f32x4){0.f, 0.f, 0.f, 0.f}); v1 = __builtin_elementwise_max(v1, (f32x4){0.f, 0.f, 0.f, 0.f}); v0 = v0 * v0; v1 = v1 * v1; }
;                     u32x4 w; w.x = pk2(v0.x, v0.y); w.y = pk2(v0.z, v0.w); w.z = pk2(v1.x, v1.y); w.w = pk2(v1.z, v1.w);
;                     if (act) __builtin_nontemporal_store(w, (u32x4*)(rowp + bj * HALF)); else *(u32x4*)(rowp + bj * HALF) = w; } }
	v_add_f32_e32 v190, v166, v167
	v_add_f32_e32 v192, v170, v171
	v_add_f32_e32 v194, v174, v175
	v_add_f32_e32 v196, v178, v179
	v_add_f32_e32 v191, v168, v169
	v_add_f32_e32 v193, v172, v173
	v_add_f32_e32 v195, v176, v177
	v_add_f32_e32 v197, v180, v181
	v_add_f32_e32 v190, v190, v191
	v_add_f32_e32 v192, v192, v193
	v_add_f32_e32 v194, v194, v195
	v_add_f32_e32 v196, v196, v197
	v_fmamk_f32 v190, v190, 0x3a800000, v154
	v_fmamk_f32 v192, v192, 0x3a800000, v154
	v_fmamk_f32 v194, v194, 0x3a800000, v154
	v_fmamk_f32 v196, v196, 0x3a800000, v154
	v_rsq_f32_e32 v190, v190
	v_rsq_f32_e32 v192, v192
	v_rsq_f32_e32 v194, v194
	v_rsq_f32_e32 v196, v196
	v_pk_mul_f32 v[62:63], v[62:63], v[190:191] op_sel_hi:[1,0]
	v_pk_mul_f32 v[60:61], v[60:61], v[190:191] op_sel_hi:[1,0]
	v_pk_mul_f32 v[58:59], v[58:59], v[190:191] op_sel_hi:[1,0]
	v_pk_mul_f32 v[56:57], v[56:57], v[190:191] op_sel_hi:[1,0]
	v_max_f32_e32 v56, 0, v56
	v_max_f32_e32 v57, 0, v57
	v_max_f32_e32 v58, 0, v58
	v_max_f32_e32 v59, 0, v59
	v_max_f32_e32 v60, 0, v60
	v_max_f32_e32 v61, 0, v61
	v_max_f32_e32 v62, 0, v62
	v_max_f32_e32 v63, 0, v63
	v_pk_mul_f32 v[62:63], v[62:63], v[62:63]
	v_pk_mul_f32 v[60:61], v[60:61], v[60:61]
	v_pk_mul_f32 v[58:59], v[58:59], v[58:59]
	v_pk_mul_f32 v[56:57], v[56:57], v[56:57]
	v_cvt_pk_bf16_f32 v200, v60, v61
	v_cvt_pk_bf16_f32 v201, v62, v63
	v_cvt_pk_bf16_f32 v202, v56, v57
	v_cvt_pk_bf16_f32 v203, v58, v59
	global_store_dwordx4 v[198:199], v[200:203], off nt
	v_pk_mul_f32 v[54:55], v[54:55], v[190:191] op_sel_hi:[1,0]
	v_pk_mul_f32 v[52:53], v[52:53], v[190:191] op_sel_hi:[1,0]
	v_pk_mul_f32 v[50:51], v[50:51], v[190:191] op_sel_hi:[1,0]
	v_pk_mul_f32 v[48:49], v[48:49], v[190:191] op_sel_hi:[1,0]
	v_max_f32_e32 v48, 0, v48
	v_max_f32_e32 v49, 0, v49
	v_max_f32_e32 v50, 0, v50
	v_max_f32_e32 v51, 0, v51
	v_max_f32_e32 v52, 0, v52
	v_max_f32_e32 v53, 0, v53
	v_max_f32_e32 v54, 0, v54
	v_max_f32_e32 v55, 0, v55
	v_pk_mul_f32 v[54:55], v[54:55], v[54:55]
	v_pk_mul_f32 v[52:53], v[52:53], v[52:53]
	v_pk_mul_f32 v[50:51], v[50:51], v[50:51]
	v_pk_mul_f32 v[48:49], v[48:49], v[48:49]
	v_cvt_pk_bf16_f32 v204, v52, v53
	v_cvt_pk_bf16_f32 v205, v54, v55
	v_cvt_pk_bf16_f32 v206, v48, v49
	v_cvt_pk_bf16_f32 v207, v50, v51
	global_store_dwordx4 v[198:199], v[204:207], off offset:256 nt
	v_lshl_add_u64 v[158:159], v[198:199], 0, s[44:45]
	v_pk_mul_f32 v[46:47], v[46:47], v[192:193] op_sel_hi:[1,0]
	v_pk_mul_f32 v[44:45], v[44:45], v[192:193] op_sel_hi:[1,0]
	v_pk_mul_f32 v[42:43], v[42:43], v[192:193] op_sel_hi:[1,0]
	v_pk_mul_f32 v[40:41], v[40:41], v[192:193] op_sel_hi:[1,0]
	v_max_f32_e32 v40, 0, v40
	v_max_f32_e32 v41, 0, v41
	v_max_f32_e32 v42, 0, v42
	v_max_f32_e32 v43, 0, v43
	v_max_f32_e32 v44, 0, v44
	v_max_f32_e32 v45, 0, v45
	v_max_f32_e32 v46, 0, v46
	v_max_f32_e32 v47, 0, v47
	v_pk_mul_f32 v[46:47], v[46:47], v[46:47]
	v_pk_mul_f32 v[44:45], v[44:45], v[44:45]
	v_pk_mul_f32 v[42:43], v[42:43], v[42:43]
	v_pk_mul_f32 v[40:41], v[40:41], v[40:41]
	v_cvt_pk_bf16_f32 v210, v44, v45
	v_cvt_pk_bf16_f32 v211, v46, v47
	v_cvt_pk_bf16_f32 v212, v40, v41
	v_cvt_pk_bf16_f32 v213, v42, v43
	global_store_dwordx4 v[158:159], v[210:213], off nt
	v_pk_mul_f32 v[38:39], v[38:39], v[192:193] op_sel_hi:[1,0]
	v_pk_mul_f32 v[36:37], v[36:37], v[192:193] op_sel_hi:[1,0]
	v_pk_mul_f32 v[34:35], v[34:35], v[192:193] op_sel_hi:[1,0]
	v_pk_mul_f32 v[32:33], v[32:33], v[192:193] op_sel_hi:[1,0]
	v_max_f32_e32 v32, 0, v32
	v_max_f32_e32 v33, 0, v33
	v_max_f32_e32 v34, 0, v34
	v_max_f32_e32 v35, 0, v35
	v_max_f32_e32 v36, 0, v36
	v_max_f32_e32 v37, 0, v37
	v_max_f32_e32 v38, 0, v38
	v_max_f32_e32 v39, 0, v39
	v_pk_mul_f32 v[38:39], v[38:39], v[38:39]
	v_pk_mul_f32 v[36:37], v[36:37], v[36:37]
; DI unsigned pk2(float lo, float hi) { f32x2 v = {lo, hi}; bf16x2_t b = __builtin_convertvector(v, bf16x2_t); return __builtin_bit_cast(unsigned, b); }
; #define PG8_BAR __builtin_amdgcn_s_barrier()
;     DI void operator()(Acc& acc, const Unit& u, int wr, int wc, int fr, int fq, LAS unsigned char*) const {
;     ...
;             for (int m = 0; m < 4; ++m) { const int row = u.pm * BM + ai * HALF + wr * 64 + m * 16 + fr; bf16_t* rowp = O + (size_t)row * ldc + col0;
;                 float rs = 1.0f; if (HAS_RS) { const f32x4 q4 = *(const f32x4*)(sumsq + (size_t)row * 4); rs = rsqrtf(((q4.x + q4.y) + (q4.z + q4.w)) * (1.0f / DM) + EPS); }
; #pragma unroll
;                 for (int bj = 0; bj < 2; ++bj) { f32x4 v0 = acc[ai][bj][m][0] * rs, v1 = acc[ai][bj][m][1] * rs;
;                     if (act) { v0 = __builtin_elementwise_max(v0, (f32x4){0.f, 0.f, 0.f, 0.f}); v1 = __builtin_elementwise_max(v1, (f32x4){0.f, 0.f, 0.f, 0.f}); v0 = v0 * v0; v1 = v1 * v1; }
;                     u32x4 w; w.x = pk2(v0.x, v0.y); w.y = pk2(v0.z, v0.w); w.z = pk2(v1.x, v1.y); w.w = pk2(v1.z, v1.w);
;                     if (act) __builtin_nontemporal_store(w, (u32x4*)(rowp + bj * HALF)); else *(u32x4*)(rowp + bj * HALF) = w; } }
; template <class GEO, class Epi>
; __device__ __forceinline__ void gemm_phase(LAS unsigned char* lds, const Gemm g, const StaticOrder& S, const Epi& E) {
;     ...
;         if (!has_next) break;
; #pragma unroll
;         for (int a = 0; a < 2; ++a)
; #pragma unroll
;             for (int b = 0; b < 2; ++b)
; #pragma unroll
;                 for (int m = 0; m < 4; ++m)
; #pragma unroll
;                     for (int n = 0; n < 2; ++n) acc[a][b][m][n] = (f32x4){0.f, 0.f, 0.f, 0.f};
;         cur = nxt; cA = nA; cB = nB; ++ui;
;         if (wr == 1) PG8_BAR;
	v_pk_mul_f32 v[34:35], v[34:35], v[34:35]
	v_pk_mul_f32 v[32:33], v[32:33], v[32:33]
	v_cvt_pk_bf16_f32 v214, v36, v37
	v_cvt_pk_bf16_f32 v215, v38, v39
	v_cvt_pk_bf16_f32 v216, v32, v33
	v_cvt_pk_bf16_f32 v217, v34, v35
	global_store_dwordx4 v[158:159], v[214:217], off offset:256 nt
	v_lshl_add_u64 v[160:161], v[158:159], 0, s[44:45]
	v_pk_mul_f32 v[30:31], v[30:31], v[194:195] op_sel_hi:[1,0]
	v_pk_mul_f32 v[28:29], v[28:29], v[194:195] op_sel_hi:[1,0]
	v_pk_mul_f32 v[26:27], v[26:27], v[194:195] op_sel_hi:[1,0]
	v_pk_mul_f32 v[24:25], v[24:25], v[194:195] op_sel_hi:[1,0]
	v_max_f32_e32 v24, 0, v24
	v_max_f32_e32 v25, 0, v25
	v_max_f32_e32 v26, 0, v26
	v_max_f32_e32 v27, 0, v27
	v_max_f32_e32 v28, 0, v28
	v_max_f32_e32 v29, 0, v29
	v_max_f32_e32 v30, 0, v30
	v_max_f32_e32 v31, 0, v31
	v_pk_mul_f32 v[30:31], v[30:31], v[30:31]
	v_pk_mul_f32 v[28:29], v[28:29], v[28:29]
	v_pk_mul_f32 v[26:27], v[26:27], v[26:27]
	v_pk_mul_f32 v[24:25], v[24:25], v[24:25]
	v_cvt_pk_bf16_f32 v200, v28, v29
	v_cvt_pk_bf16_f32 v201, v30, v31
	v_cvt_pk_bf16_f32 v202, v24, v25
	v_cvt_pk_bf16_f32 v203, v26, v27
	global_store_dwordx4 v[160:161], v[200:203], off nt
	v_pk_mul_f32 v[22:23], v[22:23], v[194:195] op_sel_hi:[1,0]
	v_pk_mul_f32 v[20:21], v[20:21], v[194:195] op_sel_hi:[1,0]
	v_pk_mul_f32 v[18:19], v[18:19], v[194:195] op_sel_hi:[1,0]
	v_pk_mul_f32 v[16:17], v[16:17], v[194:195] op_sel_hi:[1,0]
	v_max_f32_e32 v16, 0, v16
	v_max_f32_e32 v17, 0, v17
	v_max_f32_e32 v18, 0, v18
	v_max_f32_e32 v19, 0, v19
	v_max_f32_e32 v20, 0, v20
	v_max_f32_e32 v21, 0, v21
	v_max_f32_e32 v22, 0, v22
	v_max_f32_e32 v23, 0, v23
	v_pk_mul_f32 v[22:23], v[22:23], v[22:23]
	v_pk_mul_f32 v[20:21], v[20:21], v[20:21]
	v_pk_mul_f32 v[18:19], v[18:19], v[18:19]
	v_pk_mul_f32 v[16:17], v[16:17], v[16:17]
	v_cvt_pk_bf16_f32 v204, v20, v21
	v_cvt_pk_bf16_f32 v205, v22, v23
	v_cvt_pk_bf16_f32 v206, v16, v17
	v_cvt_pk_bf16_f32 v207, v18, v19
	global_store_dwordx4 v[160:161], v[204:207], off offset:256 nt
	v_lshl_add_u64 v[158:159], v[160:161], 0, s[44:45]
	v_pk_mul_f32 v[14:15], v[14:15], v[196:197] op_sel_hi:[1,0]
	v_pk_mul_f32 v[12:13], v[12:13], v[196:197] op_sel_hi:[1,0]
	v_pk_mul_f32 v[10:11], v[10:11], v[196:197] op_sel_hi:[1,0]
	v_pk_mul_f32 v[8:9], v[8:9], v[196:197] op_sel_hi:[1,0]
	v_max_f32_e32 v8, 0, v8
	v_max_f32_e32 v9, 0, v9
	v_max_f32_e32 v10, 0, v10
	v_max_f32_e32 v11, 0, v11
	v_max_f32_e32 v12, 0, v12
	v_max_f32_e32 v13, 0, v13
	v_max_f32_e32 v14, 0, v14
	v_max_f32_e32 v15, 0, v15
	v_pk_mul_f32 v[14:15], v[14:15], v[14:15]
	v_pk_mul_f32 v[12:13], v[12:13], v[12:13]
	v_pk_mul_f32 v[10:11], v[10:11], v[10:11]
	v_pk_mul_f32 v[8:9], v[8:9], v[8:9]
	v_cvt_pk_bf16_f32 v210, v12, v13
	v_cvt_pk_bf16_f32 v211, v14, v15
	v_cvt_pk_bf16_f32 v212, v8, v9
	v_cvt_pk_bf16_f32 v213, v10, v11
	global_store_dwordx4 v[158:159], v[210:213], off nt
	v_pk_mul_f32 v[6:7], v[6:7], v[196:197] op_sel_hi:[1,0]
	v_pk_mul_f32 v[4:5], v[4:5], v[196:197] op_sel_hi:[1,0]
	v_pk_mul_f32 v[2:3], v[2:3], v[196:197] op_sel_hi:[1,0]
	v_pk_mul_f32 v[0:1], v[0:1], v[196:197] op_sel_hi:[1,0]
	v_max_f32_e32 v0, 0, v0
	v_max_f32_e32 v1, 0, v1
	v_max_f32_e32 v2, 0, v2
	v_max_f32_e32 v3, 0, v3
	v_max_f32_e32 v4, 0, v4
	v_max_f32_e32 v5, 0, v5
	v_max_f32_e32 v6, 0, v6
	v_max_f32_e32 v7, 0, v7
	v_pk_mul_f32 v[6:7], v[6:7], v[6:7]
	v_pk_mul_f32 v[4:5], v[4:5], v[4:5]
	v_pk_mul_f32 v[2:3], v[2:3], v[2:3]
	v_pk_mul_f32 v[0:1], v[0:1], v[0:1]
	v_cvt_pk_bf16_f32 v214, v4, v5
	v_cvt_pk_bf16_f32 v215, v6, v7
	v_cvt_pk_bf16_f32 v216, v0, v1
	v_cvt_pk_bf16_f32 v217, v2, v3
	global_store_dwordx4 v[158:159], v[214:217], off offset:256 nt
	s_andn2_b64 vcc, exec, s[40:41]
	s_cbranch_vccnz .LBB0_1067
	s_andn2_b64 vcc, exec, s[16:17]
	s_cbranch_vccnz .LBB0_1066
	s_barrier
	s_branch .LBB0_1066
